# MoBA block-mean phase: 16 row loads in flight per iteration with counted vmcnt instead of 32 serial load-wait pairs (same accumulation order)
# speedup vs baseline: 1.0034x; 1.0034x over previous
.LBB0_1396:
	v_lshl_add_u64 v[22:23], v[8:9], 0, s[8:9]
	v_add_co_u32_e32 v24, vcc, 0x12391000, v22
	s_mov_b32 s5, 0x12391000
	s_add_u32 s8, s8, 0x4000
	v_addc_co_u32_e32 v25, vcc, 0, v23, vcc
	v_add_co_u32_e32 v22, vcc, 0x12393000, v22
	s_addc_u32 s9, s9, 0
	s_nop 0
	v_addc_co_u32_e32 v23, vcc, 0, v23, vcc
	global_load_dwordx4 v[34:37], v[24:25], off offset:-4096
	global_load_dwordx4 v[38:41], v[24:25], off offset:-3072
	global_load_dwordx4 v[42:45], v[24:25], off offset:-2048
	global_load_dwordx4 v[46:49], v[24:25], off offset:-1024
	global_load_dwordx4 v[50:53], v[24:25], off
	global_load_dwordx4 v[54:57], v[24:25], off offset:1024
	global_load_dwordx4 v[58:61], v[24:25], off offset:2048
	global_load_dwordx4 v[62:65], v[24:25], off offset:3072
	global_load_dwordx4 v[66:69], v[22:23], off offset:-4096
	global_load_dwordx4 v[70:73], v[22:23], off offset:-3072
	global_load_dwordx4 v[74:77], v[22:23], off offset:-2048
	global_load_dwordx4 v[78:81], v[22:23], off offset:-1024
	global_load_dwordx4 v[82:85], v[22:23], off
	global_load_dwordx4 v[86:89], v[22:23], off offset:1024
	global_load_dwordx4 v[90:93], v[22:23], off offset:2048
	global_load_dwordx4 v[94:97], v[22:23], off offset:3072
	s_waitcnt vmcnt(15)
	v_lshlrev_b32_e32 v18, 16, v34
	v_and_b32_e32 v19, 0xffff0000, v34
	v_lshlrev_b32_e32 v20, 16, v35
	v_and_b32_e32 v21, 0xffff0000, v35
	v_pk_add_f32 v[16:17], v[16:17], v[18:19]
	v_pk_add_f32 v[14:15], v[14:15], v[20:21]
	v_lshlrev_b32_e32 v18, 16, v36
	v_and_b32_e32 v19, 0xffff0000, v36
	v_lshlrev_b32_e32 v20, 16, v37
	v_and_b32_e32 v21, 0xffff0000, v37
	v_pk_add_f32 v[12:13], v[12:13], v[18:19]
	v_pk_add_f32 v[10:11], v[10:11], v[20:21]
	s_waitcnt vmcnt(14)
	v_lshlrev_b32_e32 v18, 16, v38
	v_and_b32_e32 v19, 0xffff0000, v38
	v_lshlrev_b32_e32 v20, 16, v39
	v_and_b32_e32 v21, 0xffff0000, v39
	v_pk_add_f32 v[16:17], v[16:17], v[18:19]
	v_pk_add_f32 v[14:15], v[14:15], v[20:21]
	v_lshlrev_b32_e32 v18, 16, v40
	v_and_b32_e32 v19, 0xffff0000, v40
	v_lshlrev_b32_e32 v20, 16, v41
	v_and_b32_e32 v21, 0xffff0000, v41
	v_pk_add_f32 v[12:13], v[12:13], v[18:19]
	v_pk_add_f32 v[10:11], v[10:11], v[20:21]
	s_waitcnt vmcnt(13)
	v_lshlrev_b32_e32 v18, 16, v42
	v_and_b32_e32 v19, 0xffff0000, v42
	v_lshlrev_b32_e32 v20, 16, v43
	v_and_b32_e32 v21, 0xffff0000, v43
	v_pk_add_f32 v[16:17], v[16:17], v[18:19]
	v_pk_add_f32 v[14:15], v[14:15], v[20:21]
	v_lshlrev_b32_e32 v18, 16, v44
	v_and_b32_e32 v19, 0xffff0000, v44
	v_lshlrev_b32_e32 v20, 16, v45
	v_and_b32_e32 v21, 0xffff0000, v45
	v_pk_add_f32 v[12:13], v[12:13], v[18:19]
	v_pk_add_f32 v[10:11], v[10:11], v[20:21]
	s_waitcnt vmcnt(12)
	v_lshlrev_b32_e32 v18, 16, v46
	v_and_b32_e32 v19, 0xffff0000, v46
	v_lshlrev_b32_e32 v20, 16, v47
	v_and_b32_e32 v21, 0xffff0000, v47
	v_pk_add_f32 v[16:17], v[16:17], v[18:19]
	v_pk_add_f32 v[14:15], v[14:15], v[20:21]
	v_lshlrev_b32_e32 v18, 16, v48
	v_and_b32_e32 v19, 0xffff0000, v48
	v_lshlrev_b32_e32 v20, 16, v49
	v_and_b32_e32 v21, 0xffff0000, v49
	v_pk_add_f32 v[12:13], v[12:13], v[18:19]
	v_pk_add_f32 v[10:11], v[10:11], v[20:21]
	s_waitcnt vmcnt(11)
	v_lshlrev_b32_e32 v18, 16, v50
	v_and_b32_e32 v19, 0xffff0000, v50
	v_lshlrev_b32_e32 v20, 16, v51
	v_and_b32_e32 v21, 0xffff0000, v51
	v_pk_add_f32 v[16:17], v[16:17], v[18:19]
	v_pk_add_f32 v[14:15], v[14:15], v[20:21]
	v_lshlrev_b32_e32 v18, 16, v52
	v_and_b32_e32 v19, 0xffff0000, v52
	v_lshlrev_b32_e32 v20, 16, v53
	v_and_b32_e32 v21, 0xffff0000, v53
	v_pk_add_f32 v[12:13], v[12:13], v[18:19]
	v_pk_add_f32 v[10:11], v[10:11], v[20:21]
	s_waitcnt vmcnt(10)
	v_lshlrev_b32_e32 v18, 16, v54
	v_and_b32_e32 v19, 0xffff0000, v54
	v_lshlrev_b32_e32 v20, 16, v55
	v_and_b32_e32 v21, 0xffff0000, v55
	v_pk_add_f32 v[16:17], v[16:17], v[18:19]
	v_pk_add_f32 v[14:15], v[14:15], v[20:21]
	v_lshlrev_b32_e32 v18, 16, v56
	v_and_b32_e32 v19, 0xffff0000, v56
	v_lshlrev_b32_e32 v20, 16, v57
	v_and_b32_e32 v21, 0xffff0000, v57
	v_pk_add_f32 v[12:13], v[12:13], v[18:19]
	v_pk_add_f32 v[10:11], v[10:11], v[20:21]
	s_waitcnt vmcnt(9)
	v_lshlrev_b32_e32 v18, 16, v58
	v_and_b32_e32 v19, 0xffff0000, v58
	v_lshlrev_b32_e32 v20, 16, v59
	v_and_b32_e32 v21, 0xffff0000, v59
	v_pk_add_f32 v[16:17], v[16:17], v[18:19]
	v_pk_add_f32 v[14:15], v[14:15], v[20:21]
	v_lshlrev_b32_e32 v18, 16, v60
	v_and_b32_e32 v19, 0xffff0000, v60
	v_lshlrev_b32_e32 v20, 16, v61
	v_and_b32_e32 v21, 0xffff0000, v61
	v_pk_add_f32 v[12:13], v[12:13], v[18:19]
	v_pk_add_f32 v[10:11], v[10:11], v[20:21]
	s_waitcnt vmcnt(8)
	v_lshlrev_b32_e32 v18, 16, v62
	v_and_b32_e32 v19, 0xffff0000, v62
	v_lshlrev_b32_e32 v20, 16, v63
	v_and_b32_e32 v21, 0xffff0000, v63
	v_pk_add_f32 v[16:17], v[16:17], v[18:19]
	v_pk_add_f32 v[14:15], v[14:15], v[20:21]
	v_lshlrev_b32_e32 v18, 16, v64
	v_and_b32_e32 v19, 0xffff0000, v64
	v_lshlrev_b32_e32 v20, 16, v65
	v_and_b32_e32 v21, 0xffff0000, v65
	v_pk_add_f32 v[12:13], v[12:13], v[18:19]
	v_pk_add_f32 v[10:11], v[10:11], v[20:21]
	s_waitcnt vmcnt(7)
	v_lshlrev_b32_e32 v18, 16, v66
	v_and_b32_e32 v19, 0xffff0000, v66
	v_lshlrev_b32_e32 v20, 16, v67
	v_and_b32_e32 v21, 0xffff0000, v67
	v_pk_add_f32 v[16:17], v[16:17], v[18:19]
	v_pk_add_f32 v[14:15], v[14:15], v[20:21]
	v_lshlrev_b32_e32 v18, 16, v68
	v_and_b32_e32 v19, 0xffff0000, v68
	v_lshlrev_b32_e32 v20, 16, v69
	v_and_b32_e32 v21, 0xffff0000, v69
	v_pk_add_f32 v[12:13], v[12:13], v[18:19]
	v_pk_add_f32 v[10:11], v[10:11], v[20:21]
	s_waitcnt vmcnt(6)
	v_lshlrev_b32_e32 v18, 16, v70
	v_and_b32_e32 v19, 0xffff0000, v70
	v_lshlrev_b32_e32 v20, 16, v71
	v_and_b32_e32 v21, 0xffff0000, v71
	v_pk_add_f32 v[16:17], v[16:17], v[18:19]
	v_pk_add_f32 v[14:15], v[14:15], v[20:21]
	v_lshlrev_b32_e32 v18, 16, v72
	v_and_b32_e32 v19, 0xffff0000, v72
	v_lshlrev_b32_e32 v20, 16, v73
	v_and_b32_e32 v21, 0xffff0000, v73
	v_pk_add_f32 v[12:13], v[12:13], v[18:19]
	v_pk_add_f32 v[10:11], v[10:11], v[20:21]
	s_waitcnt vmcnt(5)
	v_lshlrev_b32_e32 v18, 16, v74
	v_and_b32_e32 v19, 0xffff0000, v74
	v_lshlrev_b32_e32 v20, 16, v75
	v_and_b32_e32 v21, 0xffff0000, v75
	v_pk_add_f32 v[16:17], v[16:17], v[18:19]
	v_pk_add_f32 v[14:15], v[14:15], v[20:21]
	v_lshlrev_b32_e32 v18, 16, v76
	v_and_b32_e32 v19, 0xffff0000, v76
	v_lshlrev_b32_e32 v20, 16, v77
	v_and_b32_e32 v21, 0xffff0000, v77
	v_pk_add_f32 v[12:13], v[12:13], v[18:19]
	v_pk_add_f32 v[10:11], v[10:11], v[20:21]
	s_waitcnt vmcnt(4)
	v_lshlrev_b32_e32 v18, 16, v78
	v_and_b32_e32 v19, 0xffff0000, v78
	v_lshlrev_b32_e32 v20, 16, v79
	v_and_b32_e32 v21, 0xffff0000, v79
	v_pk_add_f32 v[16:17], v[16:17], v[18:19]
	v_pk_add_f32 v[14:15], v[14:15], v[20:21]
	v_lshlrev_b32_e32 v18, 16, v80
	v_and_b32_e32 v19, 0xffff0000, v80
	v_lshlrev_b32_e32 v20, 16, v81
	v_and_b32_e32 v21, 0xffff0000, v81
	v_pk_add_f32 v[12:13], v[12:13], v[18:19]
	v_pk_add_f32 v[10:11], v[10:11], v[20:21]
	s_waitcnt vmcnt(3)
	v_lshlrev_b32_e32 v18, 16, v82
	v_and_b32_e32 v19, 0xffff0000, v82
	v_lshlrev_b32_e32 v20, 16, v83
	v_and_b32_e32 v21, 0xffff0000, v83
	v_pk_add_f32 v[16:17], v[16:17], v[18:19]
	v_pk_add_f32 v[14:15], v[14:15], v[20:21]
	v_lshlrev_b32_e32 v18, 16, v84
	v_and_b32_e32 v19, 0xffff0000, v84
	v_lshlrev_b32_e32 v20, 16, v85
	v_and_b32_e32 v21, 0xffff0000, v85
	v_pk_add_f32 v[12:13], v[12:13], v[18:19]
	v_pk_add_f32 v[10:11], v[10:11], v[20:21]
	s_waitcnt vmcnt(2)
	v_lshlrev_b32_e32 v18, 16, v86
	v_and_b32_e32 v19, 0xffff0000, v86
	v_lshlrev_b32_e32 v20, 16, v87
	v_and_b32_e32 v21, 0xffff0000, v87
	v_pk_add_f32 v[16:17], v[16:17], v[18:19]
	v_pk_add_f32 v[14:15], v[14:15], v[20:21]
	v_lshlrev_b32_e32 v18, 16, v88
	v_and_b32_e32 v19, 0xffff0000, v88
	v_lshlrev_b32_e32 v20, 16, v89
	v_and_b32_e32 v21, 0xffff0000, v89
	v_pk_add_f32 v[12:13], v[12:13], v[18:19]
	v_pk_add_f32 v[10:11], v[10:11], v[20:21]
	s_waitcnt vmcnt(1)
	v_lshlrev_b32_e32 v18, 16, v90
	v_and_b32_e32 v19, 0xffff0000, v90
	v_lshlrev_b32_e32 v20, 16, v91
	v_and_b32_e32 v21, 0xffff0000, v91
	v_pk_add_f32 v[16:17], v[16:17], v[18:19]
	v_pk_add_f32 v[14:15], v[14:15], v[20:21]
	v_lshlrev_b32_e32 v18, 16, v92
	v_and_b32_e32 v19, 0xffff0000, v92
	v_lshlrev_b32_e32 v20, 16, v93
	v_and_b32_e32 v21, 0xffff0000, v93
	v_pk_add_f32 v[12:13], v[12:13], v[18:19]
	v_pk_add_f32 v[10:11], v[10:11], v[20:21]
	s_waitcnt vmcnt(0)
	v_lshlrev_b32_e32 v18, 16, v94
	v_and_b32_e32 v19, 0xffff0000, v94
	v_lshlrev_b32_e32 v20, 16, v95
	v_and_b32_e32 v21, 0xffff0000, v95
	v_pk_add_f32 v[16:17], v[16:17], v[18:19]
	v_pk_add_f32 v[14:15], v[14:15], v[20:21]
	v_lshlrev_b32_e32 v18, 16, v96
	v_and_b32_e32 v19, 0xffff0000, v96
	v_lshlrev_b32_e32 v20, 16, v97
	v_and_b32_e32 v21, 0xffff0000, v97
	v_pk_add_f32 v[12:13], v[12:13], v[18:19]
	v_pk_add_f32 v[10:11], v[10:11], v[20:21]
	s_cmpk_lg_u32 s8, 0x8000
	s_cbranch_scc1 .LBB0_1396
	ds_swizzle_b32 v0, v16 offset:swizzle(SWAP,8)
	ds_swizzle_b32 v8, v17 offset:swizzle(SWAP,8)
	ds_swizzle_b32 v9, v14 offset:swizzle(SWAP,8)
	ds_swizzle_b32 v19, v15 offset:swizzle(SWAP,8)
	ds_swizzle_b32 v20, v12 offset:swizzle(SWAP,8)
	s_waitcnt lgkmcnt(0)
	v_add_f32_e32 v0, v16, v0
	s_waitcnt lgkmcnt(3)
	v_add_f32_e32 v16, v17, v8
	ds_swizzle_b32 v8, v0 offset:swizzle(SWAP,16)
	s_waitcnt lgkmcnt(3)
	v_add_f32_e32 v14, v14, v9
	ds_swizzle_b32 v21, v13 offset:swizzle(SWAP,8)
	ds_swizzle_b32 v22, v10 offset:swizzle(SWAP,8)
	ds_swizzle_b32 v17, v16 offset:swizzle(SWAP,16)
	s_waitcnt lgkmcnt(3)
	v_add_f32_e32 v8, v0, v8
	ds_swizzle_b32 v0, v14 offset:swizzle(SWAP,16)
	s_waitcnt lgkmcnt(1)
	v_add_f32_e32 v9, v16, v17
	v_mov_b32_e32 v16, v8
	s_waitcnt lgkmcnt(0)
	v_add_f32_e32 v14, v14, v0
	v_add_f32_e32 v0, v15, v19
	ds_swizzle_b32 v15, v0 offset:swizzle(SWAP,16)
	v_mov_b32_e32 v17, v9
	v_mov_b32_e32 v18, v14
	s_waitcnt lgkmcnt(0)
	v_add_f32_e32 v15, v0, v15
	v_add_f32_e32 v0, v12, v20
	ds_swizzle_b32 v12, v0 offset:swizzle(SWAP,16)
	v_mov_b32_e32 v19, v15
	v_permlane32_swap_b32_e32 v8, v16
	s_waitcnt lgkmcnt(0)
	v_add_f32_e32 v12, v0, v12
	v_add_f32_e32 v0, v13, v21
	ds_swizzle_b32 v13, v0 offset:swizzle(SWAP,16)
	v_mov_b32_e32 v20, v12
	v_permlane32_swap_b32_e32 v9, v17
	s_waitcnt lgkmcnt(0)
	v_add_f32_e32 v13, v0, v13
	v_add_f32_e32 v0, v10, v22
	ds_swizzle_b32 v10, v0 offset:swizzle(SWAP,16)
	ds_swizzle_b32 v22, v11 offset:swizzle(SWAP,8)
	v_mov_b32_e32 v21, v13
	v_permlane32_swap_b32_e32 v14, v18
	s_waitcnt lgkmcnt(1)
	v_add_f32_e32 v10, v0, v10
	s_waitcnt lgkmcnt(0)
	v_add_f32_e32 v0, v11, v22
	ds_swizzle_b32 v11, v0 offset:swizzle(SWAP,16)
	v_mov_b32_e32 v22, v10
	v_permlane32_swap_b32_e32 v15, v19
	s_waitcnt lgkmcnt(0)
	v_add_f32_e32 v11, v0, v11
	v_mov_b32_e32 v23, v11
	v_permlane32_swap_b32_e32 v12, v20
	v_permlane32_swap_b32_e32 v13, v21
	v_permlane32_swap_b32_e32 v10, v22
	v_permlane32_swap_b32_e32 v11, v23
	s_and_saveexec_b64 s[8:9], s[40:41]
	s_cbranch_execz .LBB0_1394
	s_ashr_i32 s5, s4, 31
	s_lshl_b64 s[14:15], s[4:5], 8
	v_lshl_add_u64 v[24:25], v[2:3], 0, s[14:15]
	v_pk_add_f32 v[8:9], v[8:9], v[16:17]
	s_mov_b32 s14, 0x3b800000
	v_pk_mul_f32 v[16:17], v[8:9], s[14:15] op_sel_hi:[1,0]
	v_pk_add_f32 v[8:9], v[14:15], v[18:19]
	v_pk_add_f32 v[10:11], v[10:11], v[22:23]
	v_pk_mul_f32 v[18:19], v[8:9], s[14:15] op_sel_hi:[1,0]
	v_pk_add_f32 v[8:9], v[12:13], v[20:21]
	v_pk_mul_f32 v[10:11], v[10:11], s[14:15] op_sel_hi:[1,0]
	v_pk_mul_f32 v[8:9], v[8:9], s[14:15] op_sel_hi:[1,0]
	s_lshl_b64 s[14:15], s[4:5], 7
	global_store_dwordx4 v[24:25], v[8:11], off offset:16
	v_lshl_add_u64 v[12:13], v[6:7], 0, s[14:15]
	global_store_dwordx4 v[24:25], v[16:19], off
	v_cvt_pk_bf16_f32 v11, v10, v11
	v_cvt_pk_bf16_f32 v10, v8, v9
	v_cvt_pk_bf16_f32 v9, v18, v19
	v_cvt_pk_bf16_f32 v8, v16, v17
	global_store_dwordx4 v[12:13], v[8:11], off
	s_branch .LBB0_1394
